# first poll of each seam's wait counter issued right behind the signal (GEMM seams) or before the parameter / x loads (norm seams), so the leader does not wait for its own tile loads before it can see
# baseline (speedup 1.0000x reference)
.LBB0_265:
	v_mov_b32_e32 v0, v147
	v_readlane_b32 s2, v255, 0
	s_mov_b32 s71, s39
	v_ashrrev_i32_e32 v1, 6, v0
	v_lshl_add_u32 v96, s2, 3, v1
	s_movk_i32 s2, 0x2000
	v_cmp_gt_i32_e32 vcc, s2, v96
	s_mul_i32 s2, s70, 0xc00
	v_writelane_b32 v255, s2, 12
	s_nop 1
	v_writelane_b32 v255, s3, 13
	s_and_saveexec_b64 s[16:17], vcc
	s_cbranch_execz .LBB0_280
	s_load_dwordx4 s[8:11], s[0:1], 0x90
	s_load_dwordx4 s[12:15], s[0:1], 0x0
	s_load_dwordx4 s[4:7], s[0:1], 0x40
	s_mul_i32 s2, s70, 0x2d000
	s_mul_i32 s24, s70, 0xc00
	s_waitcnt lgkmcnt(0)
	s_add_u32 s22, s10, 0x100000
	s_addc_u32 s23, s11, 0
	s_cmp_lg_u32 s70, 0
	s_cselect_b64 s[18:19], -1, 0
	s_add_u32 s20, s22, s2
	s_mul_hi_u32 s2, s70, 0x2d000
	s_addc_u32 s21, s23, s2
	s_mov_b32 s2, s24
	v_writelane_b32 v255, s2, 12
	v_sub_u32_e64 v1, s70, 1 clamp
	v_cmp_lt_i32_e32 vcc, v188, v183
	v_writelane_b32 v255, s3, 13
	s_movk_i32 s2, 0xc00
	v_mul_lo_u32 v144, v1, s2
	s_mov_b32 s2, 0x2d000
	v_lshlrev_b64 v[2:3], 2, v[144:145]
	v_mul_lo_u32 v144, v1, s2
	v_lshlrev_b32_e32 v1, 2, v0
	v_and_b32_e32 v98, 0xfc, v1
	v_cndmask_b32_e32 v1, v182, v188, vcc
	v_cmp_lt_i32_e32 vcc, v254, v183
	v_lshlrev_b32_e32 v99, 2, v1
	v_lshl_add_u64 v[4:5], s[22:23], 0, v[144:145]
	v_cndmask_b32_e32 v1, v182, v254, vcc
	v_lshlrev_b32_e32 v128, 2, v1
	v_xor_b32_e32 v1, 4, v182
	v_cmp_lt_i32_e32 vcc, v1, v183
	v_lshlrev_b32_e32 v144, 2, v98
	s_mov_b32 s25, s39
	v_cndmask_b32_e32 v1, v182, v1, vcc
	v_lshlrev_b32_e32 v129, 2, v1
	v_xor_b32_e32 v1, 8, v182
	v_lshl_add_u64 v[2:3], s[6:7], 0, v[2:3]
	v_lshl_add_u64 v[4:5], v[4:5], 0, v[144:145]
	s_mov_b64 s[6:7], 0x8000
	v_cmp_lt_i32_e32 vcc, v1, v183
	s_lshl_b64 s[24:25], s[24:25], 2
	v_lshl_add_u64 v[100:101], v[4:5], 0, s[6:7]
	v_lshl_add_u64 v[2:3], v[2:3], 0, v[144:145]
	s_mov_b64 s[6:7], 0x2000
	v_cndmask_b32_e32 v1, v182, v1, vcc
	v_cmp_lt_i32_e32 vcc, v187, v183
	v_ashrrev_i32_e32 v97, 31, v96
	s_add_u32 s4, s4, s24
	v_lshl_add_u64 v[102:103], v[2:3], 0, s[6:7]
	v_lshlrev_b32_e32 v130, 2, v1
	v_cndmask_b32_e32 v1, v182, v187, vcc
	v_cmp_lt_i32_e32 vcc, v184, v183
	v_lshlrev_b64 v[2:3], 11, v[96:97]
	v_and_b32_e32 v4, 63, v0
	s_addc_u32 s5, s5, s25
	v_lshlrev_b32_e32 v131, 2, v1
	v_cndmask_b32_e32 v1, v182, v184, vcc
	v_lshl_or_b32 v2, v4, 3, v2
	v_lshl_add_u64 v[104:105], s[4:5], 0, v[144:145]
	v_lshlrev_b32_e32 v132, 2, v1
	v_lshl_add_u64 v[0:1], s[10:11], 0, v[2:3]
	s_mov_b64 s[4:5], 0x9800600
	v_lshlrev_b64 v[108:109], 12, v[96:97]
	v_lshl_add_u64 v[106:107], v[0:1], 0, s[4:5]
	v_lshl_or_b32 v108, v4, 4, v108
	s_mov_b64 s[10:11], 0
	s_cmp_eq_u32 s70, 0
	s_cbranch_scc1 .Lnorm0_first
	v_readlane_b32 s2, v255, 0
	v_readfirstlane_b32 s7, v147
	s_load_dwordx2 s[4:5], s[0:1], 0x90
	s_load_dwordx2 s[12:13], s[0:1], 0x98
	s_load_dwordx2 s[14:15], s[0:1], 0x40
	s_load_dwordx2 s[40:41], s[0:1], 0x48
	v_and_b32_e32 v0, 63, v147
	v_lshlrev_b32_e32 v1, 3, v0
	v_lshlrev_b32_e32 v0, 4, v0
	s_lshr_b32 s7, s7, 6
	s_and_b32 s27, s2, 6
	s_lshl_b32 s27, s27, 5
	s_and_b32 s37, s2, 0x39
	s_or_b32 s27, s27, s37
	s_lshr_b32 s37, s2, 6
	s_lshl_b32 s37, s37, 1
	s_or_b32 s2, s27, s37
	s_lshl_b32 s2, s2, 3
	s_add_u32 s2, s2, s7
	s_lshl_b32 s24, s2, 2
	s_sub_u32 s27, s24, 0x1000
	s_lshr_b32 s27, s27, 10
	s_add_u32 s27, s27, 1
	s_cmp_lt_u32 s24, 0x1000
	s_cselect_b32 s30, 0, s27
	v_add_u32_e32 v2, 0x8000, v0
	v_mov_b32_e32 v3, v0
	v_add_u32_e32 v4, 0x1000, v0
	s_waitcnt lgkmcnt(0)
	s_lshl_b32 s27, s24, 11
	s_add_u32 s62, s12, s27
	s_addc_u32 s63, s13, 0
	s_add_u32 s58, s62, 0x8800000
	s_addc_u32 s59, s63, 0
	s_add_u32 s60, s58, 0x1000000
	s_addc_u32 s61, s59, 0
	s_add_u32 s62, s62, 0x1000000
	s_addc_u32 s63, s63, 0
	s_lshl_b32 s27, s24, 12
	s_add_u32 s46, s4, s27
	s_addc_u32 s47, s5, 0
	s_mov_b64 s[4:5], s[46:47]
	s_mul_i32 s27, s70, 5
	s_add_u32 s27, s27, s30
	s_mul_i32 s27, s27, 0x9000
	s_add_u32 s27, s27, 0x100000
	s_add_u32 s88, s12, s27
	s_addc_u32 s89, s13, 0
	s_sub_u32 s100, s88, 0x2d000
	s_subb_u32 s101, s89, 0
	s_mul_i32 s27, s70, 0x3000
	s_add_u32 s27, s27, 0xfffff000
	s_add_u32 s40, s40, s27
	s_addc_u32 s41, s41, 0
	s_mul_i32 s27, s70, 0x3000
	s_add_u32 s14, s14, s27
	s_addc_u32 s15, s15, 0
	s_cmp_lg_u32 s7, 0
	s_cbranch_scc1 .Lnw_ep_n0g
	v_readlane_b32 s27, v255, 0
	s_nop 0
	s_lshr_b32 s37, s27, 3
	s_and_b32 s37, s37, 7
	s_and_b32 s27, s27, 6
	s_lshl_b32 s27, s27, 2
	s_or_b32 s27, s27, s37
	s_lshl_b32 s27, s27, 7
	s_add_u32 s27, s27, 0xa000
	v_mov_b32_e32 v18, s27
	global_load_dword v20, v18, s[12:13] sc1
.Lnw_ep_n0g:
	global_load_dwordx4 v[22:25], v2, s[100:101] offset:0
	global_load_dwordx4 v[172:175], v0, s[40:41] offset:0
	global_load_dwordx4 v[38:41], v3, s[88:89] offset:0
	global_load_dwordx4 v[54:57], v4, s[88:89] offset:0
	global_load_dwordx4 v[234:237], v0, s[14:15] offset:0
	global_load_dwordx4 v[26:29], v2, s[100:101] offset:1024
	global_load_dwordx4 v[176:179], v0, s[40:41] offset:1024
	global_load_dwordx4 v[42:45], v3, s[88:89] offset:1024
	global_load_dwordx4 v[58:61], v4, s[88:89] offset:1024
	global_load_dwordx4 v[238:241], v0, s[14:15] offset:1024
	global_load_dwordx4 v[30:33], v2, s[100:101] offset:2048
	global_load_dwordx4 v[204:207], v0, s[40:41] offset:2048
	global_load_dwordx4 v[46:49], v3, s[88:89] offset:2048
	global_load_dwordx4 v[62:65], v4, s[88:89] offset:2048
	global_load_dwordx4 v[242:245], v0, s[14:15] offset:2048
	global_load_dwordx4 v[34:37], v2, s[100:101] offset:3072
	global_load_dwordx4 v[214:217], v0, s[40:41] offset:3072
	global_load_dwordx4 v[50:53], v3, s[88:89] offset:3072
	global_load_dwordx4 v[66:69], v4, s[88:89] offset:3072
	global_load_dwordx4 v[246:249], v0, s[14:15] offset:3072
	global_load_dwordx4 v[70:73], v0, s[4:5] offset:0
	global_load_dwordx4 v[74:77], v0, s[4:5] offset:1024
	global_load_dwordx4 v[78:81], v0, s[4:5] offset:2048
	global_load_dwordx4 v[82:85], v0, s[4:5] offset:3072
	s_add_u32 s4, s4, 0x1000
	s_addc_u32 s5, s5, 0
	global_load_dwordx4 v[102:105], v0, s[4:5] offset:0
	global_load_dwordx4 v[106:109], v0, s[4:5] offset:1024
	global_load_dwordx4 v[110:113], v0, s[4:5] offset:2048
	global_load_dwordx4 v[114:117], v0, s[4:5] offset:3072
	s_add_u32 s4, s4, 0x1000
	s_addc_u32 s5, s5, 0
	global_load_dwordx4 v[154:157], v0, s[4:5] offset:0
	global_load_dwordx4 v[158:161], v0, s[4:5] offset:1024
	global_load_dwordx4 v[162:165], v0, s[4:5] offset:2048
	global_load_dwordx4 v[168:171], v0, s[4:5] offset:3072
	s_add_u32 s4, s4, 0x1000
	s_addc_u32 s5, s5, 0
	global_load_dwordx4 v[218:221], v0, s[4:5] offset:0
	global_load_dwordx4 v[222:225], v0, s[4:5] offset:1024
	global_load_dwordx4 v[226:229], v0, s[4:5] offset:2048
	global_load_dwordx4 v[230:233], v0, s[4:5] offset:3072
	s_add_u32 s4, s4, 0x1000
	s_addc_u32 s5, s5, 0
	s_waitcnt vmcnt(16)
	v_pk_mul_f32 v[22:23], v[22:23], v[172:173]
	v_pk_mul_f32 v[24:25], v[24:25], v[174:175]
	v_pk_mul_f32 v[26:27], v[26:27], v[176:177]
	v_pk_mul_f32 v[28:29], v[28:29], v[178:179]
	v_pk_mul_f32 v[30:31], v[30:31], v[204:205]
	v_pk_mul_f32 v[32:33], v[32:33], v[206:207]
	v_pk_mul_f32 v[34:35], v[34:35], v[214:215]
	v_pk_mul_f32 v[36:37], v[36:37], v[216:217]
	v_pk_add_f32 v[54:55], v[54:55], 1.0 op_sel_hi:[1,0]
	v_pk_mul_f32 v[54:55], v[54:55], v[234:235]
	v_pk_add_f32 v[56:57], v[56:57], 1.0 op_sel_hi:[1,0]
	v_pk_mul_f32 v[56:57], v[56:57], v[236:237]
	v_pk_add_f32 v[58:59], v[58:59], 1.0 op_sel_hi:[1,0]
	v_pk_mul_f32 v[58:59], v[58:59], v[238:239]
	v_pk_add_f32 v[60:61], v[60:61], 1.0 op_sel_hi:[1,0]
	v_pk_mul_f32 v[60:61], v[60:61], v[240:241]
	v_pk_add_f32 v[62:63], v[62:63], 1.0 op_sel_hi:[1,0]
	v_pk_mul_f32 v[62:63], v[62:63], v[242:243]
	v_pk_add_f32 v[64:65], v[64:65], 1.0 op_sel_hi:[1,0]
	v_pk_mul_f32 v[64:65], v[64:65], v[244:245]
	v_pk_add_f32 v[66:67], v[66:67], 1.0 op_sel_hi:[1,0]
	v_pk_mul_f32 v[66:67], v[66:67], v[246:247]
	v_pk_add_f32 v[68:69], v[68:69], 1.0 op_sel_hi:[1,0]
	v_pk_mul_f32 v[68:69], v[68:69], v[248:249]
	v_cmp_eq_u32_e32 vcc, 0, v147
	s_and_saveexec_b64 s[40:41], vcc
	s_cbranch_execz .Lnw_skip_n0g
	v_readlane_b32 s2, v255, 0
	v_readlane_b32 s7, v255, 46
	s_nop 0
	s_lshr_b32 s24, s2, 3
	s_and_b32 s24, s24, 7
	s_and_b32 s27, s2, 6
	s_lshl_b32 s27, s27, 2
	s_or_b32 s27, s27, s24
	s_lshl_b32 s27, s27, 7
	s_add_u32 s27, s27, 0xa000
	v_mov_b32_e32 v14, s27
	s_mov_b32 s30, 0
	v_readfirstlane_b32 s37, v20
	s_nop 0
	s_cmp_ge_u32 s37, s7
	s_cbranch_scc1 .Lnw_skip_n0g

.Lxb_noinv_1:
	v_cmp_eq_u32_e32 vcc, 0, v0
	s_and_saveexec_b64 s[0:1], vcc
	s_cbranch_execz .LBB0_332
	s_load_dwordx2 s[12:13], s[8:9], 0x98
	v_readlane_b32 s14, v255, 0
	v_readlane_b32 s15, v255, 48
	s_nop 0
	s_lshr_b32 s24, s14, 3
	s_and_b32 s24, s24, 7
	s_and_b32 s27, s14, 6
	s_lshl_b32 s27, s27, 2
	s_or_b32 s27, s27, s24
	s_and_b32 s30, s14, 3
	s_lshl_b32 s30, s30, 3
	s_or_b32 s30, s30, s24
	s_lshl_b32 s27, s27, 7
	s_add_u32 s27, s27, 0xc000
	v_readlane_b32 s35, v255, 45
	s_nop 0
	s_lshl_b32 s35, s35, 4
	s_add_u32 s15, s15, 8
	v_writelane_b32 v255, s15, 48
	v_mov_b32_e32 v0, s27
	s_waitcnt lgkmcnt(0)
	global_atomic_add v0, v189, s[12:13]
	v_mov_b32_e32 v26, s27
	v_mov_b32_e32 v27, 0xd000
	global_load_dword v24, v26, s[12:13] sc1
	global_load_dword v25, v27, s[12:13] sc1
	v_writelane_b32 v255, s27, 50
	v_writelane_b32 v255, s15, 51
	s_mov_b32 s34, 0xd000
	v_writelane_b32 v255, s34, 52
	v_writelane_b32 v255, s35, 53
	v_writelane_b32 v255, s12, 54
	v_writelane_b32 v255, s13, 55

.LBB0_336:
	v_readlane_b32 s26, v255, 0
	s_waitcnt vmcnt(9)
	v_mov_b32_e32 v14, v147
	s_cmpk_lt_i32 s26, 0x2c0
	v_readfirstlane_b32 s7, v14
	s_cbranch_scc0 .LBB0_352
	v_lshlrev_b32_e32 v0, 4, v14
	v_add_u32_e32 v1, 0x2000, v0
	v_ashrrev_i32_e32 v2, 31, v1
	v_lshrrev_b32_e32 v2, 22, v2
	s_load_dwordx2 s[0:1], s[8:9], 0x98
	v_add_u32_e32 v2, v1, v2
	v_ashrrev_i32_e32 v8, 10, v2
	v_mul_i32_i24_e32 v2, 0x400, v8
	v_sub_u32_e32 v1, v1, v2
	s_mul_i32 s5, s70, 0x2800000
	v_lshrrev_b32_e32 v2, 4, v1
	s_waitcnt lgkmcnt(0)
	s_add_u32 s5, s0, s5
	v_bitop3_b32 v1, v2, v1, 32 bitop3:0x6c
	s_addc_u32 s6, s1, 0
	v_ashrrev_i32_e32 v2, 31, v1
	s_add_u32 s27, s0, 0x1000000
	v_lshrrev_b32_e32 v2, 26, v2
	s_mul_i32 s4, s2, 0xb00000
	s_addc_u32 s30, s1, 0
	v_add_u32_e32 v2, v1, v2
	v_lshlrev_b32_e32 v3, 3, v8
	s_add_u32 s4, s5, s4
	v_ashrrev_i32_e32 v9, 6, v2
	v_and_b32_e32 v3, -16, v3
	s_addc_u32 s5, s6, 0
	v_add_u32_e32 v3, v9, v3
	s_add_u32 s31, s4, 0xc800000
	v_and_b32_e32 v4, 3, v9
	s_mov_b32 s4, 0x1fffe0
	v_lshrrev_b32_e32 v5, 2, v3
	v_lshlrev_b32_e32 v6, 1, v3
	v_and_b32_e32 v2, 0xc0, v2
	v_and_or_b32 v4, v3, s4, v4
	v_and_b32_e32 v5, 4, v5
	v_and_b32_e32 v6, 24, v6
	v_sub_u32_e32 v1, v1, v2
	v_or3_b32 v4, v4, v5, v6
	v_lshlrev_b32_e32 v5, 5, v8
	v_ashrrev_i16_sdwa v1, v189, sext(v1) dst_sel:DWORD dst_unused:UNUSED_PAD src0_sel:DWORD src1_sel:BYTE_0
	v_and_b32_e32 v5, 32, v5
	v_bfe_i32 v10, v1, 0, 16
	v_add_lshl_u32 v1, v5, v10, 1
	v_lshl_add_u32 v128, v4, 11, v1
	v_lshl_add_u32 v130, v3, 11, v1
	v_bfe_i32 v1, v14, 27, 1
	v_lshrrev_b32_e32 v1, 22, v1
	v_add_u32_e32 v1, v0, v1
	v_and_b32_e32 v1, 0xfffffc00, v1
	v_sub_u32_e32 v0, v0, v1
	v_lshrrev_b32_e32 v1, 4, v0
	v_bitop3_b32 v1, v1, v0, 32 bitop3:0x6c
	v_ashrrev_i32_e32 v0, 31, v0
	v_lshrrev_b32_e32 v0, 26, v0
	v_add_u32_e32 v0, v1, v0
	v_ashrrev_i32_e32 v11, 6, v0
	v_ashrrev_i32_e32 v0, 31, v14
	v_lshrrev_b32_e32 v0, 26, v0
	v_add_u32_e32 v0, v14, v0
	v_ashrrev_i32_e32 v12, 6, v0
	v_lshlrev_b32_e32 v0, 3, v12
	v_and_b32_e32 v0, -16, v0
	s_addc_u32 s33, s5, 0
	v_add_u32_e32 v0, v11, v0
	v_and_b32_e32 v2, 3, v11
	s_ashr_i32 s37, s26, 31
	v_and_or_b32 v2, v0, s4, v2
	s_lshr_b32 s4, s37, 29
	s_add_i32 s4, s26, s4
	s_ashr_i32 s12, s7, 6
	s_ashr_i32 s5, s4, 3
	s_and_b32 s4, s4, -8
	s_ashr_i32 s13, s7, 8
	s_lshl_b32 s36, s12, 10
	s_sub_i32 s4, s26, s4
	s_cmp_lt_i32 s4, 0
	s_movk_i32 s6, 0x59
	s_cselect_b32 s6, s6, 0x58
	s_mul_i32 s4, s4, s6
	s_add_i32 s4, s4, s5
	s_mul_hi_i32 s5, s4, 0x2e8ba2e9
	s_lshr_b32 s6, s5, 31
	s_ashr_i32 s5, s5, 5
	s_add_i32 s5, s5, s6
	s_lshl_b32 s14, s5, 3
	s_mulk_i32 s5, 0xb0
	s_sub_i32 s4, s4, s5
	s_bfe_u32 s5, s4, 0x3001c
	s_add_i32 s5, s4, s5
	s_sext_i32_i16 s6, s5
	s_and_b32 s5, s5, 0xfff8
	s_sub_i32 s4, s4, s5
	s_sext_i32_i16 s4, s4
	s_add_i32 s5, s14, s4
	s_ashr_i32 s4, s5, 31
	s_lshr_b32 s4, s4, 27
	s_add_i32 s14, s5, s4
	s_ashr_i32 s4, s14, 5
	s_andn2_b32 s14, s14, 31
	s_sub_i32 s24, s5, s14
	s_ashr_i32 s5, s4, 31
	s_ashr_i32 s25, s24, 31
	s_lshr_b32 s6, s6, 3
	s_lshl_b64 s[4:5], s[4:5], 11
	s_lshl_b64 s[14:15], s[24:25], 19
	v_lshrrev_b32_e32 v3, 2, v0
	v_lshlrev_b32_e32 v4, 1, v0
	s_add_u32 s16, s27, s14
	v_and_b32_e32 v3, 4, v3
	v_and_b32_e32 v4, 24, v4
	s_addc_u32 s17, s30, s15
	s_bfe_i64 s[14:15], s[6:7], 0x100000
	v_or3_b32 v2, v2, v3, v4
	v_mul_i32_i24_e32 v4, 64, v11
	s_lshl_b64 s[14:15], s[14:15], 19
	v_sub_u32_e32 v1, v1, v4
	s_add_u32 s14, s31, s14
	v_lshlrev_b32_e32 v3, 5, v12
	v_ashrrev_i16_sdwa v1, v189, sext(v1) dst_sel:DWORD dst_unused:UNUSED_PAD src0_sel:DWORD src1_sel:BYTE_0
	s_addc_u32 s15, s33, s15
	v_and_b32_e32 v3, 32, v3
	s_waitcnt vmcnt(7)
	v_bfe_i32 v13, v1, 0, 16
	s_add_u32 s42, s14, s4
	v_add_lshl_u32 v1, v3, v13, 1
	s_addc_u32 s43, s15, s5
	s_add_i32 s38, s36, 0
	v_lshl_add_u32 v144, v2, 11, v1
	s_add_i32 m0, s38, 0x10000
	v_lshl_add_u32 v132, v0, 11, v1
	global_load_lds_dwordx4 v144, s[42:43]
	s_add_i32 m0, s38, 0x12000
	s_add_u32 s14, s42, 0x40000
	global_load_lds_dwordx4 v128, s[42:43]
	s_addc_u32 s15, s43, 0
	s_add_i32 m0, s38, 0x14000
	v_mov_b32_e32 v129, v145
	global_load_lds_dwordx4 v144, s[14:15]
	s_add_i32 m0, s38, 0x16000
	s_add_u32 s54, s16, s4
	s_addc_u32 s55, s17, s5
	s_add_i32 s40, s38, 0x2000
	global_load_lds_dwordx4 v128, s[14:15]
	v_cmp_eq_u32_e32 vcc, 0, v147
	s_and_saveexec_b64 s[100:101], vcc
	s_cbranch_execz .Lgw_skip_fi
	v_readlane_b32 s56, v255, 54
	v_readlane_b32 s57, v255, 55
	v_readlane_b32 s58, v255, 50
	v_readlane_b32 s59, v255, 51
	v_readlane_b32 s60, v255, 52
	v_readlane_b32 s61, v255, 53
	s_mov_b32 s62, 0
	s_waitcnt vmcnt(4)
	v_readfirstlane_b32 s63, v24
	v_readfirstlane_b32 s82, v25
	s_nop 0
	s_cmp_ge_u32 s63, s59
	s_cselect_b32 s63, 1, 0
	s_cmp_ge_u32 s82, s61
	s_cselect_b32 s82, 1, 0
	s_and_b32 s63, s63, s82
	s_cmp_lg_u32 s63, 0
	s_cbranch_scc1 .Lgw_skip_fi
	s_nop 1
	v_mov_b32_e32 v20, s58
	v_mov_b32_e32 v21, s60
	s_nop 1

.Lgs_nocw_b2:
	v_mov_b32_e32 v26, s30
	v_mov_b32_e32 v27, s30
	global_load_dword v24, v26, s[12:13] sc1
	global_load_dword v25, v27, s[12:13] sc1
	v_writelane_b32 v255, s30, 50
	v_writelane_b32 v255, s15, 51
	v_writelane_b32 v255, s30, 52
	v_writelane_b32 v255, s15, 53
	v_writelane_b32 v255, s12, 54
	v_writelane_b32 v255, s13, 55

.LBB0_443:
	v_ashrrev_i32_e32 v1, 31, v8
	v_lshrrev_b32_e32 v1, 26, v1
	v_add_u32_e32 v1, v8, v1
	v_ashrrev_i32_e32 v9, 6, v1
	v_bfe_i32 v1, v8, 27, 1
	v_lshlrev_b32_e32 v0, 4, v8
	v_lshrrev_b32_e32 v1, 22, v1
	v_add_u32_e32 v1, v0, v1
	v_and_b32_e32 v1, 0xfffffc00, v1
	v_sub_u32_e32 v1, v0, v1
	s_mul_i32 s6, s2, 0x580000
	s_mul_i32 s2, s70, 0x2800000
	v_lshrrev_b32_e32 v2, 4, v1
	s_waitcnt lgkmcnt(0)
	s_add_u32 s9, s4, s2
	v_bitop3_b32 v2, v2, v1, 32 bitop3:0x6c
	v_ashrrev_i32_e32 v1, 31, v1
	s_addc_u32 s13, s5, 0
	v_lshrrev_b32_e32 v1, 26, v1
	s_add_u32 s2, s4, 0x5800000
	v_lshlrev_b32_e32 v3, 3, v9
	v_add_u32_e32 v1, v2, v1
	s_addc_u32 s30, s5, 0
	v_and_b32_e32 v3, -16, v3
	v_ashrrev_i32_e32 v11, 6, v1
	s_add_u32 s6, s9, s6
	v_add_u32_e32 v1, v11, v3
	v_lshlrev_b32_e32 v3, 5, v9
	s_addc_u32 s9, s13, 0
	v_and_b32_e32 v10, 32, v3
	v_mul_i32_i24_e32 v3, 64, v11
	s_add_u32 s31, s6, 0xde00000
	v_sub_u32_e32 v2, v2, v3
	s_addc_u32 s33, s9, 0
	v_ashrrev_i16_sdwa v2, v189, sext(v2) dst_sel:DWORD dst_unused:UNUSED_PAD src0_sel:DWORD src1_sel:BYTE_0
	v_lshlrev_b32_e32 v3, 1, v1
	v_lshrrev_b32_e32 v4, 2, v1
	v_and_b32_e32 v5, 3, v11
	s_mov_b32 s9, 0xffffe0
	v_bfe_i32 v12, v2, 0, 16
	v_and_b32_e32 v3, 24, v3
	v_and_b32_e32 v4, 4, v4
	v_and_or_b32 v5, v1, s9, v5
	s_movk_i32 s13, 0xb00
	v_add_u32_e32 v2, v10, v12
	v_or3_b32 v3, v5, v4, v3
	v_mul_lo_u32 v1, v1, s13
	v_add_lshl_u32 v128, v2, v1, 1
	v_mul_u32_u24_e32 v1, 0xb00, v3
	v_add_u32_e32 v0, 0x2000, v0
	v_add_lshl_u32 v130, v1, v2, 1
	v_ashrrev_i32_e32 v1, 31, v0
	v_lshrrev_b32_e32 v1, 22, v1
	v_add_u32_e32 v1, v0, v1
	v_ashrrev_i32_e32 v13, 10, v1
	v_mul_i32_i24_e32 v1, 0x400, v13
	v_sub_u32_e32 v0, v0, v1
	v_lshrrev_b32_e32 v1, 4, v0
	v_bitop3_b32 v0, v1, v0, 32 bitop3:0x6c
	v_ashrrev_i32_e32 v2, 31, v0
	v_lshrrev_b32_e32 v2, 26, v2
	s_add_i32 s7, s8, s7
	v_lshlrev_b32_e32 v1, 3, v13
	v_add_u32_e32 v2, v0, v2
	s_ashr_i32 s8, s7, 31
	v_and_b32_e32 v1, -16, v1
	v_ashrrev_i32_e32 v15, 6, v2
	s_lshr_b32 s8, s8, 27
	v_add_u32_e32 v1, v15, v1
	v_and_b32_e32 v4, 3, v15
	s_add_i32 s8, s7, s8
	v_and_or_b32 v4, v1, s9, v4
	s_ashr_i32 s9, s8, 5
	s_and_b32 s8, s8, 0xffe0
	s_sub_i32 s8, s7, s8
	s_bfe_i32 s7, s8, 0x80000
	s_bfe_u32 s7, s7, 0x3000c
	s_add_i32 s14, s8, s7
	s_bfe_i32 s7, s14, 0x80000
	s_and_b32 s14, s14, 0xf8
	s_sub_i32 s8, s8, s14
	s_lshl_b32 s9, s9, 3
	s_sext_i32_i8 s8, s8
	s_add_i32 s8, s9, s8
	s_ashr_i32 s9, s8, 31
	s_lshr_b32 s9, s9, 27
	s_add_i32 s9, s8, s9
	s_ashr_i32 s16, s9, 5
	s_andn2_b32 s9, s9, 31
	v_lshlrev_b32_e32 v3, 5, v13
	v_and_b32_e32 v2, 0xc0, v2
	s_sext_i32_i16 s15, s7
	s_sub_i32 s54, s8, s9
	v_and_b32_e32 v14, 32, v3
	v_sub_u32_e32 v0, v0, v2
	v_lshlrev_b32_e32 v2, 1, v1
	v_lshrrev_b32_e32 v3, 2, v1
	v_mul_lo_u32 v1, v1, s13
	s_ashr_i32 s13, s12, 6
	s_lshr_b32 s7, s15, 3
	s_mul_i32 s8, s54, 0x160000
	s_ashr_i32 s15, s15, 3
	s_ashr_i32 s6, s12, 8
	s_lshl_b32 s36, s13, 10
	s_ashr_i32 s9, s8, 31
	s_mul_hi_i32 s18, s15, 0x160000
	s_mul_i32 s15, s15, 0x160000
	s_add_u32 s15, s31, s15
	s_mul_i32 s17, s16, 0xb00
	s_addc_u32 s18, s33, s18
	s_mul_hi_i32 s14, s16, 0xb00
	s_add_u32 s20, s15, s17
	s_addc_u32 s21, s18, s14
	s_add_i32 s37, s36, 0
	v_ashrrev_i16_sdwa v0, v189, sext(v0) dst_sel:DWORD dst_unused:UNUSED_PAD src0_sel:DWORD src1_sel:BYTE_0
	s_add_i32 m0, s37, 0x10000
	v_bfe_i32 v16, v0, 0, 16
	v_and_b32_e32 v2, 24, v2
	v_and_b32_e32 v3, 4, v3
	global_load_lds_dwordx4 v130, s[20:21]
	s_add_i32 m0, s37, 0x12000
	v_add_u32_e32 v0, v14, v16
	v_or3_b32 v2, v4, v3, v2
	s_add_u32 s15, s2, s8
	v_add_lshl_u32 v132, v0, v1, 1
	v_mul_u32_u24_e32 v1, 0xb00, v2
	s_addc_u32 s19, s30, s9
	v_add_lshl_u32 v134, v1, v0, 1
	s_add_u32 s8, s20, 0xb0000
	global_load_lds_dwordx4 v134, s[20:21]
	s_addc_u32 s9, s21, 0
	s_add_i32 m0, s37, 0x14000
	v_mov_b32_e32 v131, v145
	global_load_lds_dwordx4 v130, s[8:9]
	s_add_i32 m0, s37, 0x16000
	s_add_u32 s18, s15, s17
	s_addc_u32 s19, s19, s14
	s_add_i32 s40, s37, 0x2000
	global_load_lds_dwordx4 v134, s[8:9]
	v_cmp_eq_u32_e32 vcc, 0, v147
	s_and_saveexec_b64 s[100:101], vcc
	s_cbranch_execz .Lgw_skip_fo
	v_readlane_b32 s56, v255, 54
	v_readlane_b32 s57, v255, 55
	v_readlane_b32 s58, v255, 50
	v_readlane_b32 s59, v255, 51
	v_readlane_b32 s60, v255, 52
	v_readlane_b32 s61, v255, 53
	s_mov_b32 s62, 0
	s_waitcnt vmcnt(4)
	v_readfirstlane_b32 s63, v24
	v_readfirstlane_b32 s82, v25
	s_nop 0
	s_cmp_ge_u32 s63, s59
	s_cselect_b32 s63, 1, 0
	s_cmp_ge_u32 s82, s61
	s_cselect_b32 s82, 1, 0
	s_and_b32 s63, s63, s82
	s_cmp_lg_u32 s63, 0
	s_cbranch_scc1 .Lgw_skip_fo
	s_nop 1
	v_mov_b32_e32 v20, s58
	v_mov_b32_e32 v21, s60
	s_nop 1

.LBB0_519:
	s_or_b64 exec, exec, s[4:5]
	s_mov_b64 s[4:5], -1
	v_writelane_b32 v255, s4, 19
	s_and_b64 vcc, exec, s[10:11]
	s_waitcnt lgkmcnt(0)
	v_writelane_b32 v255, s5, 20
	s_mov_b64 s[4:5], -1
	s_barrier
	s_cbranch_vccz .LBB0_335
	s_mov_b64 s[16:17], s[0:1]
	v_mov_b32_e32 v0, v147
	v_readlane_b32 s2, v255, 0
	s_nop 0
	v_ashrrev_i32_e32 v1, 6, v0
	v_lshl_add_u32 v16, s2, 3, v1
	s_movk_i32 s2, 0x2000
	v_cmp_gt_i32_e32 vcc, s2, v16
	s_and_saveexec_b64 s[8:9], vcc
	s_cbranch_execz .LBB0_523
	s_load_dwordx4 s[4:7], s[16:17], 0x90
	s_load_dwordx4 s[12:15], s[16:17], 0x40
	v_lshlrev_b32_e32 v1, 2, v0
	v_cmp_lt_i32_e32 vcc, v188, v183
	v_and_b32_e32 v2, 0xfc, v1
	s_mul_i32 s2, s70, 0x2d000
	v_cndmask_b32_e32 v1, v182, v188, vcc
	v_cmp_lt_i32_e32 vcc, v254, v183
	s_waitcnt lgkmcnt(0)
	s_add_u32 s18, s6, s2
	s_mul_hi_u32 s2, s70, 0x2d000
	v_lshlrev_b32_e32 v28, 2, v1
	v_cndmask_b32_e32 v1, v182, v254, vcc
	s_addc_u32 s19, s7, s2
	v_readlane_b32 s20, v255, 12
	v_lshlrev_b32_e32 v29, 2, v1
	v_xor_b32_e32 v1, 4, v182
	s_add_u32 s10, s18, 0x103000
	v_readlane_b32 s21, v255, 13
	v_cmp_lt_i32_e32 vcc, v1, v183
	s_addc_u32 s11, s19, 0
	s_lshl_b64 s[20:21], s[20:21], 2
	v_cndmask_b32_e32 v1, v182, v1, vcc
	s_add_u32 s12, s12, s20
	v_lshlrev_b32_e32 v144, 2, v2
	v_lshlrev_b32_e32 v30, 2, v1
	v_xor_b32_e32 v1, 8, v182
	s_addc_u32 s13, s13, s21
	v_lshl_add_u64 v[4:5], s[18:19], 0, v[144:145]
	s_mov_b64 s[18:19], 0x102000
	v_cmp_lt_i32_e32 vcc, v1, v183
	v_lshl_add_u64 v[18:19], v[4:5], 0, s[18:19]
	v_lshl_add_u64 v[4:5], s[12:13], 0, v[144:145]
	v_cndmask_b32_e32 v1, v182, v1, vcc
	v_cmp_lt_i32_e32 vcc, v187, v183
	v_ashrrev_i32_e32 v17, 31, v16
	v_lshl_add_u64 v[22:23], v[4:5], 0, s[94:95]
	v_lshlrev_b32_e32 v31, 2, v1
	v_cndmask_b32_e32 v1, v182, v187, vcc
	v_cmp_lt_i32_e32 vcc, v184, v183
	v_lshlrev_b64 v[4:5], 11, v[16:17]
	v_and_b32_e32 v3, 63, v0
	v_lshlrev_b32_e32 v32, 2, v1
	v_cndmask_b32_e32 v1, v182, v184, vcc
	v_lshl_or_b32 v4, v3, 3, v4
	v_lshlrev_b32_e32 v33, 2, v1
	v_lshl_add_u64 v[0:1], s[6:7], 0, v[4:5]
	s_mov_b64 s[6:7], 0x9800600
	s_add_u32 s14, s14, s20
	v_lshl_add_u64 v[24:25], v[0:1], 0, s[6:7]
	v_lshlrev_b64 v[0:1], 12, v[16:17]
	s_addc_u32 s15, s15, s21
	v_lshl_or_b32 v0, v3, 4, v0
	v_lshl_add_u64 v[20:21], s[14:15], 0, v[144:145]
	v_lshl_add_u64 v[26:27], s[4:5], 0, v[0:1]
	s_mov_b64 s[4:5], 0
	v_lshlrev_b32_e32 v144, 2, v2
	v_readlane_b32 s2, v255, 0
	v_readfirstlane_b32 s7, v147
	s_load_dwordx2 s[4:5], s[16:17], 0x90
	s_load_dwordx2 s[12:13], s[16:17], 0x98
	s_load_dwordx2 s[14:15], s[16:17], 0x40
	s_load_dwordx2 s[40:41], s[16:17], 0x48
	v_and_b32_e32 v0, 63, v147
	v_lshlrev_b32_e32 v1, 3, v0
	v_lshlrev_b32_e32 v0, 4, v0
	s_lshr_b32 s7, s7, 6
	s_and_b32 s27, s2, 6
	s_lshl_b32 s27, s27, 5
	s_and_b32 s37, s2, 0x39
	s_or_b32 s27, s27, s37
	s_lshr_b32 s37, s2, 6
	s_lshl_b32 s37, s37, 1
	s_or_b32 s2, s27, s37
	s_lshl_b32 s2, s2, 3
	s_add_u32 s2, s2, s7
	s_lshl_b32 s24, s2, 2
	s_sub_u32 s27, s24, 0x1000
	s_lshr_b32 s27, s27, 10
	s_add_u32 s27, s27, 1
	s_cmp_lt_u32 s24, 0x1000
	s_cselect_b32 s30, 0, s27
	v_add_u32_e32 v2, 0x2000, v0
	v_add_u32_e32 v3, 0x3000, v0
	v_add_u32_e32 v4, 0x4000, v0
	s_waitcnt lgkmcnt(0)
	s_lshl_b32 s27, s24, 11
	s_add_u32 s62, s12, s27
	s_addc_u32 s63, s13, 0
	s_add_u32 s58, s62, 0x8800000
	s_addc_u32 s59, s63, 0
	s_add_u32 s60, s58, 0x1000000
	s_addc_u32 s61, s59, 0
	s_add_u32 s62, s62, 0x1000000
	s_addc_u32 s63, s63, 0
	s_lshl_b32 s27, s24, 12
	s_add_u32 s46, s4, s27
	s_addc_u32 s47, s5, 0
	s_mov_b64 s[4:5], s[46:47]
	s_mul_i32 s27, s70, 5
	s_add_u32 s27, s27, s30
	s_mul_i32 s27, s27, 0x9000
	s_add_u32 s27, s27, 0x100000
	s_add_u32 s88, s12, s27
	s_addc_u32 s89, s13, 0
	s_mov_b64 s[100:101], s[88:89]
	s_mul_i32 s27, s70, 0x3000
	s_add_u32 s40, s40, s27
	s_addc_u32 s41, s41, 0
	s_mul_i32 s27, s70, 0x3000
	s_add_u32 s27, s27, 0x1000
	s_add_u32 s14, s14, s27
	s_addc_u32 s15, s15, 0
	s_cmp_lg_u32 s7, 0
	s_cbranch_scc1 .Lnw_ep_n1
	v_readlane_b32 s27, v255, 0
	s_nop 0
	s_lshr_b32 s37, s27, 3
	s_and_b32 s37, s37, 7
	s_and_b32 s27, s27, 6
	s_lshl_b32 s27, s27, 2
	s_or_b32 s27, s27, s37
	s_lshl_b32 s27, s27, 7
	s_add_u32 s27, s27, 0xa000
	v_mov_b32_e32 v18, s27
	global_load_dword v20, v18, s[12:13] sc1

.Lxb_noinv_4:
	v_cmp_eq_u32_e32 vcc, 0, v0
	s_and_saveexec_b64 s[4:5], vcc
	s_cbranch_execz .LBB0_575
	s_load_dwordx2 s[12:13], s[16:17], 0x98
	v_readlane_b32 s14, v255, 0
	v_readlane_b32 s15, v255, 47
	s_nop 0
	s_lshr_b32 s24, s14, 3
	s_and_b32 s24, s24, 7
	s_and_b32 s27, s14, 6
	s_lshl_b32 s27, s27, 2
	s_or_b32 s27, s27, s24
	s_and_b32 s30, s14, 3
	s_lshl_b32 s30, s30, 3
	s_or_b32 s30, s30, s24
	s_lshl_b32 s27, s27, 7
	s_add_u32 s27, s27, 0xb000
	s_add_u32 s15, s15, 8
	v_writelane_b32 v255, s15, 47
	v_mov_b32_e32 v0, s27
	s_waitcnt lgkmcnt(0)
	global_atomic_add v0, v189, s[12:13]
	v_mov_b32_e32 v26, s27
	v_mov_b32_e32 v27, s27
	global_load_dword v24, v26, s[12:13] sc1
	global_load_dword v25, v27, s[12:13] sc1
	v_writelane_b32 v255, s27, 50
	v_writelane_b32 v255, s15, 51
	v_writelane_b32 v255, s27, 52
	v_writelane_b32 v255, s15, 53
	v_writelane_b32 v255, s12, 54
	v_writelane_b32 v255, s13, 55

.LBB0_581:
	s_andn2_b64 vcc, exec, s[10:11]
	s_cbranch_vccnz .LBB0_921
	v_ashrrev_i32_e32 v1, 31, v10
	v_lshrrev_b32_e32 v1, 26, v1
	v_add_u32_e32 v1, v10, v1
	v_ashrrev_i32_e32 v8, 6, v1
	v_bfe_i32 v1, v10, 27, 1
	v_lshlrev_b32_e32 v0, 4, v10
	v_lshrrev_b32_e32 v1, 22, v1
	v_add_u32_e32 v1, v0, v1
	v_and_b32_e32 v1, 0xfffffc00, v1
	v_sub_u32_e32 v1, v0, v1
	v_lshrrev_b32_e32 v2, 4, v1
	v_bitop3_b32 v2, v2, v1, 32 bitop3:0x6c
	v_ashrrev_i32_e32 v1, 31, v1
	v_lshrrev_b32_e32 v1, 26, v1
	v_add_u32_e32 v1, v2, v1
	s_mul_i32 s7, s70, 0x2800000
	v_ashrrev_i32_e32 v9, 6, v1
	s_waitcnt lgkmcnt(0)
	s_add_u32 s7, s14, s7
	v_lshlrev_b32_e32 v3, 3, v8
	v_mul_i32_i24_e32 v4, 64, v9
	s_addc_u32 s9, s15, 0
	v_and_b32_e32 v3, -16, v3
	v_sub_u32_e32 v2, v2, v4
	s_add_u32 s51, s14, 0x1000000
	v_add_u32_e32 v1, v9, v3
	v_lshlrev_b32_e32 v3, 5, v8
	v_ashrrev_i16_sdwa v2, v189, sext(v2) dst_sel:DWORD dst_unused:UNUSED_PAD src0_sel:DWORD src1_sel:BYTE_0
	s_addc_u32 s71, s15, 0
	v_and_b32_e32 v3, 32, v3
	v_bfe_i32 v11, v2, 0, 16
	s_add_u32 s78, s7, 0xe900000
	v_and_b32_e32 v5, 3, v9
	s_mov_b32 s7, 0x1fffe0
	v_add_lshl_u32 v3, v3, v11, 1
	v_add_u32_e32 v0, 0x2000, v0
	v_lshlrev_b32_e32 v2, 1, v1
	v_lshrrev_b32_e32 v4, 2, v1
	v_and_or_b32 v5, v1, s7, v5
	v_lshl_add_u32 v132, v1, 11, v3
	v_ashrrev_i32_e32 v1, 31, v0
	v_lshrrev_b32_e32 v1, 22, v1
	v_add_u32_e32 v1, v0, v1
	v_ashrrev_i32_e32 v12, 10, v1
	v_mul_i32_i24_e32 v1, 0x400, v12
	v_sub_u32_e32 v0, v0, v1
	v_and_b32_e32 v2, 24, v2
	v_and_b32_e32 v4, 4, v4
	v_lshrrev_b32_e32 v1, 4, v0
	v_or3_b32 v2, v5, v4, v2
	v_bitop3_b32 v0, v1, v0, 32 bitop3:0x6c
	v_lshl_add_u32 v134, v2, 11, v3
	v_ashrrev_i32_e32 v2, 31, v0
	v_lshrrev_b32_e32 v2, 26, v2
	v_lshlrev_b32_e32 v1, 3, v12
	v_add_u32_e32 v2, v0, v2
	v_and_b32_e32 v1, -16, v1
	v_ashrrev_i32_e32 v13, 6, v2
	v_add_u32_e32 v1, v13, v1
	v_and_b32_e32 v4, 3, v13
	s_addc_u32 s79, s9, 0
	v_and_or_b32 v4, v1, s7, v4
	s_ashr_i32 s11, s2, 6
	s_ashr_i32 s7, s6, 31
	s_ashr_i32 s10, s2, 8
	s_lshl_b32 s86, s11, 10
	s_lshl_b64 s[18:19], s[6:7], 19
	s_add_u32 s7, s51, s18
	s_addc_u32 s20, s71, s19
	s_ashr_i32 s9, s8, 31
	s_lshl_b64 s[18:19], s[8:9], 19
	v_and_b32_e32 v2, 0xc0, v2
	s_add_u32 s9, s78, s18
	v_sub_u32_e32 v0, v0, v2
	s_addc_u32 s18, s79, s19
	v_ashrrev_i16_sdwa v0, v189, sext(v0) dst_sel:DWORD dst_unused:UNUSED_PAD src0_sel:DWORD src1_sel:BYTE_0
	s_add_u32 s42, s9, s4
	v_lshlrev_b32_e32 v3, 5, v12
	v_bfe_i32 v14, v0, 0, 16
	v_lshlrev_b32_e32 v0, 1, v1
	v_lshrrev_b32_e32 v2, 2, v1
	s_addc_u32 s43, s18, s5
	s_add_i32 s87, s86, 0
	v_and_b32_e32 v3, 32, v3
	v_and_b32_e32 v0, 24, v0
	v_and_b32_e32 v2, 4, v2
	s_add_i32 m0, s87, 0x10000
	v_or3_b32 v0, v4, v2, v0
	v_add_lshl_u32 v2, v3, v14, 1
	global_load_lds_dwordx4 v134, s[42:43]
	s_add_i32 m0, s87, 0x12000
	v_lshl_add_u32 v138, v0, 11, v2
	s_add_u32 s18, s42, 0x40000
	global_load_lds_dwordx4 v138, s[42:43]
	s_addc_u32 s19, s43, 0
	s_add_i32 m0, s87, 0x14000
	v_lshl_add_u32 v136, v1, 11, v2
	global_load_lds_dwordx4 v134, s[18:19]
	s_add_i32 m0, s87, 0x16000
	s_add_u32 s4, s7, s4
	s_addc_u32 s5, s20, s5
	s_add_i32 s76, s87, 0x2000
	global_load_lds_dwordx4 v138, s[18:19]
	v_cmp_eq_u32_e32 vcc, 0, v147
	s_and_saveexec_b64 s[100:101], vcc
	s_cbranch_execz .Lgw_skip_mi
	v_readlane_b32 s56, v255, 54
	v_readlane_b32 s57, v255, 55
	v_readlane_b32 s58, v255, 50
	v_readlane_b32 s59, v255, 51
	v_readlane_b32 s60, v255, 52
	v_readlane_b32 s61, v255, 53
	s_mov_b32 s62, 0
	s_waitcnt vmcnt(4)
	v_readfirstlane_b32 s63, v24
	v_readfirstlane_b32 s82, v25
	s_nop 0
	s_cmp_ge_u32 s63, s59
	s_cselect_b32 s63, 1, 0
	s_cmp_ge_u32 s82, s61
	s_cselect_b32 s82, 1, 0
	s_and_b32 s63, s63, s82
	s_cmp_lg_u32 s63, 0
	s_cbranch_scc1 .Lgw_skip_mi
	s_nop 1
	v_mov_b32_e32 v20, s58
	v_mov_b32_e32 v21, s60
	s_nop 1

.LBB0_1222:
	s_or_b64 exec, exec, s[4:5]
	s_waitcnt lgkmcnt(0)
	v_mov_b32_e32 v0, v147
	v_readlane_b32 s2, v255, 0
	s_barrier
	s_nop 0
	v_ashrrev_i32_e32 v1, 6, v0
	v_lshl_add_u32 v16, s2, 3, v1
	s_movk_i32 s2, 0x2000
	v_cmp_gt_i32_e32 vcc, s2, v16
	s_and_saveexec_b64 s[10:11], vcc
	s_cbranch_execz .LBB0_1225
	s_load_dwordx4 s[4:7], s[8:9], 0x90
	s_load_dwordx4 s[16:19], s[8:9], 0x40
	s_mul_i32 s2, s70, 0x2d000
	v_lshlrev_b32_e32 v1, 2, v0
	v_readlane_b32 s20, v255, 12
	s_waitcnt lgkmcnt(0)
	s_add_u32 s14, s6, s2
	s_mul_hi_u32 s2, s70, 0x2d000
	s_addc_u32 s15, s7, s2
	v_cmp_lt_i32_e32 vcc, v188, v183
	v_and_b32_e32 v2, 0xfc, v1
	s_add_u32 s12, s14, 0x106000
	v_readlane_b32 s21, v255, 13
	v_cndmask_b32_e32 v1, v182, v188, vcc
	v_cmp_lt_i32_e32 vcc, v254, v183
	s_addc_u32 s13, s15, 0
	s_lshl_b64 s[20:21], s[20:21], 2
	v_lshlrev_b32_e32 v28, 2, v1
	v_cndmask_b32_e32 v1, v182, v254, vcc
	s_add_u32 s16, s16, s20
	v_lshlrev_b32_e32 v29, 2, v1
	v_xor_b32_e32 v1, 4, v182
	s_addc_u32 s17, s17, s21
	v_cmp_lt_i32_e32 vcc, v1, v183
	s_add_u32 s18, s18, s20
	v_lshlrev_b32_e32 v144, 2, v2
	v_cndmask_b32_e32 v1, v182, v1, vcc
	s_addc_u32 s19, s19, s21
	v_lshl_add_u64 v[4:5], s[14:15], 0, v[144:145]
	s_mov_b64 s[14:15], 0x105000
	v_lshlrev_b32_e32 v30, 2, v1
	v_xor_b32_e32 v1, 8, v182
	v_lshl_add_u64 v[18:19], v[4:5], 0, s[14:15]
	v_lshl_add_u64 v[4:5], s[18:19], 0, v[144:145]
	v_cmp_lt_i32_e32 vcc, v1, v183
	v_lshl_add_u64 v[20:21], v[4:5], 0, s[94:95]
	v_lshl_add_u64 v[4:5], s[16:17], 0, v[144:145]
	s_mov_b64 s[14:15], 0x2000
	v_cndmask_b32_e32 v1, v182, v1, vcc
	v_cmp_lt_i32_e32 vcc, v187, v183
	v_ashrrev_i32_e32 v17, 31, v16
	v_lshl_add_u64 v[22:23], v[4:5], 0, s[14:15]
	v_lshlrev_b32_e32 v31, 2, v1
	v_cndmask_b32_e32 v1, v182, v187, vcc
	v_cmp_lt_i32_e32 vcc, v184, v183
	v_lshlrev_b64 v[4:5], 11, v[16:17]
	v_and_b32_e32 v3, 63, v0
	v_lshlrev_b32_e32 v32, 2, v1
	v_cndmask_b32_e32 v1, v182, v184, vcc
	v_lshl_or_b32 v4, v3, 3, v4
	v_lshlrev_b32_e32 v33, 2, v1
	v_lshl_add_u64 v[0:1], s[6:7], 0, v[4:5]
	s_mov_b64 s[6:7], 0x9800600
	v_lshl_add_u64 v[24:25], v[0:1], 0, s[6:7]
	v_lshlrev_b64 v[0:1], 12, v[16:17]
	v_lshl_or_b32 v0, v3, 4, v0
	v_lshl_add_u64 v[26:27], s[4:5], 0, v[0:1]
	s_mov_b64 s[4:5], 0
	v_lshlrev_b32_e32 v144, 2, v2
	v_readlane_b32 s2, v255, 0
	v_readfirstlane_b32 s7, v147
	s_load_dwordx2 s[4:5], s[8:9], 0x90
	s_load_dwordx2 s[12:13], s[8:9], 0x98
	s_load_dwordx2 s[14:15], s[8:9], 0x40
	s_load_dwordx2 s[40:41], s[8:9], 0x48
	v_and_b32_e32 v0, 63, v147
	v_lshlrev_b32_e32 v1, 3, v0
	v_lshlrev_b32_e32 v0, 4, v0
	s_lshr_b32 s7, s7, 6
	s_and_b32 s27, s2, 6
	s_lshl_b32 s27, s27, 5
	s_and_b32 s37, s2, 0x39
	s_or_b32 s27, s27, s37
	s_lshr_b32 s37, s2, 6
	s_lshl_b32 s37, s37, 1
	s_or_b32 s2, s27, s37
	s_lshl_b32 s2, s2, 3
	s_add_u32 s2, s2, s7
	s_lshl_b32 s24, s2, 2
	s_sub_u32 s27, s24, 0x1000
	s_lshr_b32 s27, s27, 10
	s_add_u32 s27, s27, 1
	s_cmp_lt_u32 s24, 0x1000
	s_cselect_b32 s30, 0, s27
	v_add_u32_e32 v2, 0x5000, v0
	v_add_u32_e32 v3, 0x6000, v0
	v_add_u32_e32 v4, 0x7000, v0
	s_waitcnt lgkmcnt(0)
	s_lshl_b32 s27, s24, 11
	s_add_u32 s62, s12, s27
	s_addc_u32 s63, s13, 0
	s_add_u32 s58, s62, 0x8800000
	s_addc_u32 s59, s63, 0
	s_add_u32 s60, s58, 0x1000000
	s_addc_u32 s61, s59, 0
	s_add_u32 s62, s62, 0x1000000
	s_addc_u32 s63, s63, 0
	s_lshl_b32 s27, s24, 12
	s_add_u32 s46, s4, s27
	s_addc_u32 s47, s5, 0
	s_mov_b64 s[4:5], s[46:47]
	s_mul_i32 s27, s70, 5
	s_add_u32 s27, s27, s30
	s_mul_i32 s27, s27, 0x9000
	s_add_u32 s27, s27, 0x100000
	s_add_u32 s88, s12, s27
	s_addc_u32 s89, s13, 0
	s_mov_b64 s[100:101], s[88:89]
	s_mul_i32 s27, s70, 0x3000
	s_add_u32 s27, s27, 0x1000
	s_add_u32 s40, s40, s27
	s_addc_u32 s41, s41, 0
	s_mul_i32 s27, s70, 0x3000
	s_add_u32 s27, s27, 0x2000
	s_add_u32 s14, s14, s27
	s_addc_u32 s15, s15, 0
	s_cmp_lg_u32 s7, 0
	s_cbranch_scc1 .Lnw_ep_n2
	v_readlane_b32 s27, v255, 0
	s_nop 0
	s_lshr_b32 s37, s27, 3
	s_and_b32 s37, s37, 7
	s_and_b32 s27, s27, 6
	s_lshl_b32 s27, s27, 2
	s_or_b32 s27, s27, s37
	s_lshl_b32 s27, s27, 7
	s_add_u32 s27, s27, 0xa000
	v_mov_b32_e32 v18, s27
	global_load_dword v20, v18, s[12:13] sc1

.Lxb_noinv_8:
	v_cmp_eq_u32_e32 vcc, 0, v0
	s_and_saveexec_b64 s[4:5], vcc
	s_cbranch_execz .Ltramp_334
	s_load_dwordx2 s[12:13], s[8:9], 0x98
	v_readlane_b32 s14, v255, 0
	v_readlane_b32 s15, v255, 47
	s_nop 0
	s_lshr_b32 s24, s14, 3
	s_and_b32 s24, s24, 7
	s_and_b32 s27, s14, 6
	s_lshl_b32 s27, s27, 2
	s_or_b32 s27, s27, s24
	s_and_b32 s30, s14, 3
	s_lshl_b32 s30, s30, 3
	s_or_b32 s30, s30, s24
	s_lshl_b32 s27, s27, 7
	s_add_u32 s27, s27, 0xb000
	s_add_u32 s15, s15, 8
	v_writelane_b32 v255, s15, 47
	v_mov_b32_e32 v0, s27
	s_waitcnt lgkmcnt(0)
	global_atomic_add v0, v189, s[12:13]
	v_mov_b32_e32 v26, s27
	v_mov_b32_e32 v27, s27
	global_load_dword v24, v26, s[12:13] sc1
	global_load_dword v25, v27, s[12:13] sc1
	v_writelane_b32 v255, s27, 50
	v_writelane_b32 v255, s15, 51
	v_writelane_b32 v255, s27, 52
	v_writelane_b32 v255, s15, 53
	v_writelane_b32 v255, s12, 54
	v_writelane_b32 v255, s13, 55
	s_branch .LBB0_334
.LBB0_1276:
	v_readlane_b32 s2, v255, 0
	s_nop 0
	v_ashrrev_i32_e32 v0, 6, v147
	v_lshl_add_u32 v32, s2, 3, v0
	s_movk_i32 s2, 0x2000
	v_cmp_gt_i32_e32 vcc, s2, v32
	s_and_saveexec_b64 s[2:3], vcc
	s_cbranch_execz .LBB0_1279
	v_readlane_b32 s2, v255, 0
	v_readfirstlane_b32 s7, v147
	s_load_dwordx2 s[4:5], s[0:1], 0x90
	s_load_dwordx2 s[12:13], s[0:1], 0x98
	s_load_dwordx2 s[40:41], s[0:1], 0x48
	v_and_b32_e32 v0, 63, v147
	v_lshlrev_b32_e32 v1, 3, v0
	v_lshlrev_b32_e32 v0, 4, v0
	s_lshr_b32 s7, s7, 6
	s_and_b32 s27, s2, 6
	s_lshl_b32 s27, s27, 5
	s_and_b32 s37, s2, 0x39
	s_or_b32 s27, s27, s37
	s_lshr_b32 s37, s2, 6
	s_lshl_b32 s37, s37, 1
	s_or_b32 s2, s27, s37
	s_lshl_b32 s2, s2, 3
	s_add_u32 s2, s2, s7
	s_lshl_b32 s24, s2, 2
	s_sub_u32 s27, s24, 0x1000
	s_lshr_b32 s27, s27, 10
	s_add_u32 s27, s27, 1
	s_cmp_lt_u32 s24, 0x1000
	s_cselect_b32 s30, 0, s27
	v_add_u32_e32 v2, 0x8000, v0
	v_mov_b32_e32 v3, v0
	v_add_u32_e32 v4, 0x1000, v0
	s_waitcnt lgkmcnt(0)
	s_lshl_b32 s27, s24, 11
	s_add_u32 s62, s12, s27
	s_addc_u32 s63, s13, 0
	s_add_u32 s58, s62, 0x8800000
	s_addc_u32 s59, s63, 0
	s_add_u32 s60, s58, 0x1000000
	s_addc_u32 s61, s59, 0
	s_add_u32 s62, s62, 0x1000000
	s_addc_u32 s63, s63, 0
	s_lshl_b32 s27, s24, 12
	s_add_u32 s46, s4, s27
	s_addc_u32 s47, s5, 0
	s_mov_b64 s[4:5], s[46:47]
	s_add_u32 s27, s30, 15
	s_mul_i32 s27, s27, 0x9000
	s_add_u32 s27, s27, 0x100000
	s_add_u32 s88, s12, s27
	s_addc_u32 s89, s13, 0
	s_mov_b64 s[100:101], s[88:89]
	s_mov_b32 s27, 0xb000
	s_add_u32 s40, s40, s27
	s_addc_u32 s41, s41, 0
	s_cmp_lg_u32 s7, 0
	s_cbranch_scc1 .Lnw_ep_n3
	v_readlane_b32 s27, v255, 0
	s_nop 0
	s_lshr_b32 s37, s27, 3
	s_and_b32 s37, s37, 7
	s_and_b32 s27, s27, 6
	s_lshl_b32 s27, s27, 2
	s_or_b32 s27, s27, s37
	s_lshl_b32 s27, s27, 7
	s_add_u32 s27, s27, 0xa000
	v_mov_b32_e32 v18, s27
	global_load_dword v20, v18, s[12:13] sc1
.Lnw_ep_n3:
	global_load_dwordx4 v[22:25], v2, s[100:101] offset:0
	global_load_dwordx4 v[118:121], v0, s[40:41] offset:0
	global_load_dwordx4 v[26:29], v2, s[100:101] offset:1024
	global_load_dwordx4 v[122:125], v0, s[40:41] offset:1024
	global_load_dwordx4 v[30:33], v2, s[100:101] offset:2048
	global_load_dwordx4 v[134:137], v0, s[40:41] offset:2048
	global_load_dwordx4 v[34:37], v2, s[100:101] offset:3072
	global_load_dwordx4 v[138:141], v0, s[40:41] offset:3072
	global_load_dwordx4 v[38:41], v0, s[4:5] offset:0
	global_load_dwordx4 v[42:45], v0, s[4:5] offset:1024
	global_load_dwordx4 v[46:49], v0, s[4:5] offset:2048
	global_load_dwordx4 v[50:53], v0, s[4:5] offset:3072
	s_add_u32 s4, s4, 0x1000
	s_addc_u32 s5, s5, 0
	global_load_dwordx4 v[70:73], v0, s[4:5] offset:0
	global_load_dwordx4 v[74:77], v0, s[4:5] offset:1024
	global_load_dwordx4 v[78:81], v0, s[4:5] offset:2048
	global_load_dwordx4 v[82:85], v0, s[4:5] offset:3072
	s_add_u32 s4, s4, 0x1000
	s_addc_u32 s5, s5, 0
	global_load_dwordx4 v[102:105], v0, s[4:5] offset:0
	global_load_dwordx4 v[106:109], v0, s[4:5] offset:1024
	global_load_dwordx4 v[110:113], v0, s[4:5] offset:2048
	global_load_dwordx4 v[114:117], v0, s[4:5] offset:3072
	s_add_u32 s4, s4, 0x1000
	s_addc_u32 s5, s5, 0
	global_load_dwordx4 v[154:157], v0, s[4:5] offset:0
	global_load_dwordx4 v[158:161], v0, s[4:5] offset:1024
	global_load_dwordx4 v[162:165], v0, s[4:5] offset:2048
	global_load_dwordx4 v[168:171], v0, s[4:5] offset:3072
	s_add_u32 s4, s4, 0x1000
	s_addc_u32 s5, s5, 0
	s_waitcnt vmcnt(16)
	v_pk_mul_f32 v[22:23], v[22:23], v[118:119]
	v_pk_mul_f32 v[24:25], v[24:25], v[120:121]
	v_pk_mul_f32 v[26:27], v[26:27], v[122:123]
	v_pk_mul_f32 v[28:29], v[28:29], v[124:125]
	v_pk_mul_f32 v[30:31], v[30:31], v[134:135]
	v_pk_mul_f32 v[32:33], v[32:33], v[136:137]
	v_pk_mul_f32 v[34:35], v[34:35], v[138:139]
	v_pk_mul_f32 v[36:37], v[36:37], v[140:141]
	v_cmp_eq_u32_e32 vcc, 0, v147
	s_and_saveexec_b64 s[40:41], vcc
	s_cbranch_execz .Lnw_skip_n3
	v_readlane_b32 s2, v255, 0
	v_readlane_b32 s7, v255, 46
	s_nop 0
	s_lshr_b32 s24, s2, 3
	s_and_b32 s24, s24, 7
	s_and_b32 s27, s2, 6
	s_lshl_b32 s27, s27, 2
	s_or_b32 s27, s27, s24
	s_lshl_b32 s27, s27, 7
	s_add_u32 s27, s27, 0xa000
	v_mov_b32_e32 v14, s27
	s_mov_b32 s30, 0
	v_readfirstlane_b32 s37, v20
	s_nop 0
	s_cmp_ge_u32 s37, s7
	s_cbranch_scc1 .Lnw_skip_n3
